# attention: bias lookups of a sub-block issued before the QK MFMAs, logits computed after one wait (regenerated QK block)
# baseline (speedup 1.0000x reference)
.LBB0_136:
	v_mov_b32_e32 v129, v72
	s_waitcnt vmcnt(15)
	ds_write_b128 v117, v[88:91]
	s_waitcnt vmcnt(14)
	ds_write_b128 v117, v[92:95] offset:1056
	s_waitcnt vmcnt(13)
	ds_write_b128 v117, v[96:99] offset:2112
	s_waitcnt vmcnt(12)
	ds_write_b128 v117, v[144:147] offset:3168
	s_waitcnt vmcnt(11)
	ds_write_b128 v117, v[152:155] offset:4224
	s_waitcnt vmcnt(10)
	ds_write_b128 v117, v[156:159] offset:5280
	s_waitcnt vmcnt(9)
	ds_write_b128 v117, v[160:163] offset:6336
	s_waitcnt vmcnt(8)
	ds_write_b128 v117, v[172:175] offset:7392
	s_waitcnt vmcnt(7)
	ds_write_b128 v117, v[192:195] offset:8448
	s_waitcnt vmcnt(6)
	ds_write_b128 v117, v[132:135] offset:9504
	s_waitcnt vmcnt(5)
	ds_write_b128 v117, v[136:139] offset:10560
	s_waitcnt vmcnt(4)
	ds_write_b128 v117, v[140:143] offset:11616
	s_waitcnt vmcnt(3)
	ds_write_b128 v117, v[228:231] offset:12672
	s_waitcnt vmcnt(2)
	ds_write_b128 v117, v[232:235] offset:13728
	s_waitcnt vmcnt(1)
	ds_write_b128 v117, v[236:239] offset:14784
	s_waitcnt vmcnt(0)
	ds_write_b128 v117, v[240:243] offset:15840
	v_subrev_u32_e32 v88, s29, v164
	v_med3_i32 v88, v88, s4, v189
	v_lshl_add_u32 v88, v88, 6, v116
	v_subrev_u32_e32 v89, s29, v166
	v_med3_i32 v89, v89, s4, v189
	v_lshl_add_u32 v89, v89, 6, v116
	v_subrev_u32_e32 v90, s29, v168
	v_med3_i32 v90, v90, s4, v189
	v_lshl_add_u32 v90, v90, 6, v116
	v_subrev_u32_e32 v91, s29, v169
	v_med3_i32 v91, v91, s4, v189
	v_lshl_add_u32 v91, v91, 6, v116
	v_subrev_u32_e32 v92, s29, v170
	v_med3_i32 v92, v92, s4, v189
	v_lshl_add_u32 v92, v92, 6, v116
	v_subrev_u32_e32 v93, s29, v176
	v_med3_i32 v93, v93, s4, v189
	v_lshl_add_u32 v93, v93, 6, v116
	v_subrev_u32_e32 v94, s29, v177
	v_med3_i32 v94, v94, s4, v189
	v_lshl_add_u32 v94, v94, 6, v116
	v_subrev_u32_e32 v95, s29, v191
	v_med3_i32 v95, v95, s4, v189
	v_lshl_add_u32 v95, v95, 6, v116
	ds_read_b32 v88, v88 offset:8192
	ds_read_b32 v89, v89 offset:8192
	ds_read_b32 v90, v90 offset:8192
	ds_read_b32 v91, v91 offset:8192
	ds_read_b32 v92, v92 offset:8192
	ds_read_b32 v93, v93 offset:8192
	ds_read_b32 v94, v94 offset:8192
	ds_read_b32 v95, v95 offset:8192
	ds_read_b128 v[228:231], v118
	ds_read_b128 v[232:235], v118 offset:64
	ds_read_b128 v[236:239], v118 offset:128
	ds_read_b128 v[240:243], v118 offset:192
	s_waitcnt lgkmcnt(3)
	v_mfma_f32_16x16x32_bf16 v[134:137], v[228:231], v[196:199], 0
	ds_read_b128 v[228:231], v118 offset:256
	s_waitcnt lgkmcnt(3)
	v_mfma_f32_16x16x32_bf16 v[134:137], v[232:235], v[200:203], v[134:137]
	ds_read_b128 v[232:235], v118 offset:320
	s_waitcnt lgkmcnt(3)
	v_mfma_f32_16x16x32_bf16 v[134:137], v[236:239], v[204:207], v[134:137]
	ds_read_b128 v[236:239], v118 offset:384
	s_waitcnt lgkmcnt(3)
	v_mfma_f32_16x16x32_bf16 v[134:137], v[240:243], v[208:211], v[134:137]
	ds_read_b128 v[240:243], v118 offset:448
	s_waitcnt lgkmcnt(3)
	v_mfma_f32_16x16x32_bf16 v[134:137], v[228:231], v[212:215], v[134:137]
	ds_read_b128 v[228:231], v118 offset:8448
	s_waitcnt lgkmcnt(3)
	v_mfma_f32_16x16x32_bf16 v[134:137], v[232:235], v[216:219], v[134:137]
	ds_read_b128 v[232:235], v118 offset:8512
	s_waitcnt lgkmcnt(3)
	v_mfma_f32_16x16x32_bf16 v[134:137], v[236:239], v[220:223], v[134:137]
	ds_read_b128 v[236:239], v118 offset:8576
	s_waitcnt lgkmcnt(3)
	v_mfma_f32_16x16x32_bf16 v[134:137], v[240:243], v[224:227], v[134:137]
	ds_read_b128 v[240:243], v118 offset:8640
	s_waitcnt lgkmcnt(3)
	v_mfma_f32_16x16x32_bf16 v[72:75], v[228:231], v[196:199], 0
	ds_read_b128 v[228:231], v118 offset:8704
	s_waitcnt lgkmcnt(3)
	v_mfma_f32_16x16x32_bf16 v[72:75], v[232:235], v[200:203], v[72:75]
	ds_read_b128 v[232:235], v118 offset:8768
	s_waitcnt lgkmcnt(3)
	v_mfma_f32_16x16x32_bf16 v[72:75], v[236:239], v[204:207], v[72:75]
	ds_read_b128 v[236:239], v118 offset:8832
	s_waitcnt lgkmcnt(3)
	v_mfma_f32_16x16x32_bf16 v[72:75], v[240:243], v[208:211], v[72:75]
	ds_read_b128 v[240:243], v118 offset:8896
	s_waitcnt lgkmcnt(3)
	v_mfma_f32_16x16x32_bf16 v[72:75], v[228:231], v[212:215], v[72:75]
	s_waitcnt lgkmcnt(2)
	v_mfma_f32_16x16x32_bf16 v[72:75], v[232:235], v[216:219], v[72:75]
	s_waitcnt lgkmcnt(1)
	v_mfma_f32_16x16x32_bf16 v[72:75], v[236:239], v[220:223], v[72:75]
	s_waitcnt lgkmcnt(0)
	v_mfma_f32_16x16x32_bf16 v[72:75], v[240:243], v[224:227], v[72:75]
	s_nop 7
	v_fmac_f32_e32 v88, 0x3d800000, v134
	v_fmac_f32_e32 v89, 0x3d800000, v135
	v_fmac_f32_e32 v90, 0x3d800000, v136
	v_fmac_f32_e32 v91, 0x3d800000, v137
	s_nop 3
	v_fmac_f32_e32 v92, 0x3d800000, v72
	v_fmac_f32_e32 v93, 0x3d800000, v73
	v_fmac_f32_e32 v94, 0x3d800000, v74
	v_fmac_f32_e32 v95, 0x3d800000, v75
	v_cmp_lt_i32_e64 s[0:1], -1, v164
	v_cmp_lt_i32_e64 s[2:3], -1, v166
	v_cmp_lt_i32_e64 vcc, -1, v168
	v_cndmask_b32_e64 v76, v190, v88, s[0:1]
	v_cndmask_b32_e64 v77, v190, v89, s[2:3]
	v_cndmask_b32_e64 v78, v190, v90, vcc
	v_cmp_lt_i32_e64 s[0:1], -1, v169
	v_cmp_lt_i32_e64 s[2:3], -1, v170
	v_cmp_lt_i32_e64 vcc, -1, v176
	v_cndmask_b32_e64 v79, v190, v91, s[0:1]
	v_cndmask_b32_e64 v72, v190, v92, s[2:3]
	v_cndmask_b32_e64 v80, v190, v93, vcc
	v_cmp_lt_i32_e64 s[0:1], -1, v177
	v_cmp_lt_i32_e64 s[2:3], -1, v191
	s_nop 1
	v_cndmask_b32_e64 v74, v190, v94, s[0:1]
	v_cndmask_b32_e64 v75, v190, v95, s[2:3]
	v_max_f32_e32 v81, v78, v79
	s_add_i32 s2, s30, 1
	s_cmp_eq_u32 s2, 8
	s_cbranch_scc1 .Latt_nopf
	s_lshr_b32 s3, s2, 1
	s_cmp_eq_u32 s3, 2
	s_cselect_b64 vcc, -1, 0
	v_cndmask_b32_e32 v244, v127, v126, vcc
	s_cmp_eq_u32 s3, 1
	s_cselect_b64 vcc, -1, 0
	v_cndmask_b32_e32 v244, v244, v125, vcc
	s_cmp_eq_u32 s3, 0
	s_cselect_b64 vcc, -1, 0
	v_cndmask_b32_e32 v244, v244, v124, vcc
	s_bitcmp1_b32 s2, 0
	v_readfirstlane_b32 s2, v108
	v_readfirstlane_b32 s3, v109
	s_cbranch_scc1 .Latt_pf_odd
	v_readlane_b32 s0, v244, 0
	v_readlane_b32 s1, v244, 1
	v_readlane_b32 vcc_lo, v244, 2
	v_readlane_b32 vcc_hi, v244, 3
	s_mov_b32 exec_lo, 0xffff
	s_mov_b32 exec_hi, 0x0
	v_mov_b32_e32 v164, s0
	v_mov_b32_e32 v166, s1
	v_mov_b32_e32 v168, vcc_lo
	v_mov_b32_e32 v169, vcc_hi
	s_mov_b64 exec, -1
	s_max_i32 s0, s0, 0
	s_max_i32 s1, s1, 0
	s_max_i32 vcc_lo, vcc_lo, 0
	s_max_i32 vcc_hi, vcc_hi, 0
	s_sub_i32 s1, s1, s0
	s_sub_i32 vcc_hi, vcc_hi, vcc_lo
	s_lshl_b32 s0, s0, 9
	s_lshl_b32 s1, s1, 9
	s_lshl_b32 vcc_lo, vcc_lo, 9
	s_lshl_b32 vcc_hi, vcc_hi, 9
	v_add_u32_e32 v88, s0, v246
	v_add_u32_e32 v92, vcc_lo, v246
	v_mad_i32_i24 v88, v115, s1, v88
	v_mad_i32_i24 v92, v115, vcc_hi, v92
	global_load_dwordx4 v[88:91], v88, s[2:3]
	global_load_dwordx4 v[92:95], v92, s[2:3]
	v_readlane_b32 s0, v244, 4
	v_readlane_b32 s1, v244, 5
	v_readlane_b32 vcc_lo, v244, 6
	v_readlane_b32 vcc_hi, v244, 7
	s_mov_b32 exec_lo, 0xffff0000
	s_mov_b32 exec_hi, 0x0
	v_mov_b32_e32 v164, s0
	v_mov_b32_e32 v166, s1
	v_mov_b32_e32 v168, vcc_lo
	v_mov_b32_e32 v169, vcc_hi
	s_mov_b64 exec, -1
	s_max_i32 s0, s0, 0
	s_max_i32 s1, s1, 0
	s_max_i32 vcc_lo, vcc_lo, 0
	s_max_i32 vcc_hi, vcc_hi, 0
	s_sub_i32 s1, s1, s0
	s_sub_i32 vcc_hi, vcc_hi, vcc_lo
	s_lshl_b32 s0, s0, 9
	s_lshl_b32 s1, s1, 9
	s_lshl_b32 vcc_lo, vcc_lo, 9
	s_lshl_b32 vcc_hi, vcc_hi, 9
	v_add_u32_e32 v96, s0, v246
	v_add_u32_e32 v144, vcc_lo, v246
	v_mad_i32_i24 v96, v115, s1, v96
	v_mad_i32_i24 v144, v115, vcc_hi, v144
	global_load_dwordx4 v[96:99], v96, s[2:3]
	global_load_dwordx4 v[144:147], v144, s[2:3]
	v_readlane_b32 s0, v244, 8
	v_readlane_b32 s1, v244, 9
	v_readlane_b32 vcc_lo, v244, 10
	v_readlane_b32 vcc_hi, v244, 11
	s_mov_b32 exec_lo, 0x0
	s_mov_b32 exec_hi, 0xffff
	v_mov_b32_e32 v164, s0
	v_mov_b32_e32 v166, s1
	v_mov_b32_e32 v168, vcc_lo
	v_mov_b32_e32 v169, vcc_hi
	s_mov_b64 exec, -1
	s_max_i32 s0, s0, 0
	s_max_i32 s1, s1, 0
	s_max_i32 vcc_lo, vcc_lo, 0
	s_max_i32 vcc_hi, vcc_hi, 0
	s_sub_i32 s1, s1, s0
	s_sub_i32 vcc_hi, vcc_hi, vcc_lo
	s_lshl_b32 s0, s0, 9
	s_lshl_b32 s1, s1, 9
	s_lshl_b32 vcc_lo, vcc_lo, 9
	s_lshl_b32 vcc_hi, vcc_hi, 9
	v_add_u32_e32 v152, s0, v246
	v_add_u32_e32 v156, vcc_lo, v246
	v_mad_i32_i24 v152, v115, s1, v152
	v_mad_i32_i24 v156, v115, vcc_hi, v156
	global_load_dwordx4 v[152:155], v152, s[2:3]
	global_load_dwordx4 v[156:159], v156, s[2:3]
	v_readlane_b32 s0, v244, 12
	v_readlane_b32 s1, v244, 13
	v_readlane_b32 vcc_lo, v244, 14
	v_readlane_b32 vcc_hi, v244, 15
	s_mov_b32 exec_lo, 0x0
	s_mov_b32 exec_hi, 0xffff0000
	v_mov_b32_e32 v164, s0
	v_mov_b32_e32 v166, s1
	v_mov_b32_e32 v168, vcc_lo
	v_mov_b32_e32 v169, vcc_hi
	s_mov_b64 exec, -1
	s_max_i32 s0, s0, 0
	s_max_i32 s1, s1, 0
	s_max_i32 vcc_lo, vcc_lo, 0
	s_max_i32 vcc_hi, vcc_hi, 0
	s_sub_i32 s1, s1, s0
	s_sub_i32 vcc_hi, vcc_hi, vcc_lo
	s_lshl_b32 s0, s0, 9
	s_lshl_b32 s1, s1, 9
	s_lshl_b32 vcc_lo, vcc_lo, 9
	s_lshl_b32 vcc_hi, vcc_hi, 9
	v_add_u32_e32 v160, s0, v246
	v_add_u32_e32 v172, vcc_lo, v246
	v_mad_i32_i24 v160, v115, s1, v160
	v_mad_i32_i24 v172, v115, vcc_hi, v172
	global_load_dwordx4 v[160:163], v160, s[2:3]
	global_load_dwordx4 v[172:175], v172, s[2:3]
	v_readlane_b32 s0, v244, 16
	v_readlane_b32 s1, v244, 17
	v_readlane_b32 vcc_lo, v244, 18
	v_readlane_b32 vcc_hi, v244, 19
	s_mov_b32 exec_lo, 0xffff
	s_mov_b32 exec_hi, 0x0
	v_mov_b32_e32 v170, s0
	v_mov_b32_e32 v176, s1
	v_mov_b32_e32 v177, vcc_lo
	v_mov_b32_e32 v191, vcc_hi
	s_mov_b64 exec, -1
	s_max_i32 s0, s0, 0
	s_max_i32 s1, s1, 0
	s_max_i32 vcc_lo, vcc_lo, 0
	s_max_i32 vcc_hi, vcc_hi, 0
	s_sub_i32 s1, s1, s0
	s_sub_i32 vcc_hi, vcc_hi, vcc_lo
	s_lshl_b32 s0, s0, 9
	s_lshl_b32 s1, s1, 9
	s_lshl_b32 vcc_lo, vcc_lo, 9
	s_lshl_b32 vcc_hi, vcc_hi, 9
	v_add_u32_e32 v192, s0, v246
	v_add_u32_e32 v132, vcc_lo, v246
	v_mad_i32_i24 v192, v115, s1, v192
	v_mad_i32_i24 v132, v115, vcc_hi, v132
	global_load_dwordx4 v[192:195], v192, s[2:3]
	global_load_dwordx4 v[132:135], v132, s[2:3]
	v_readlane_b32 s0, v244, 20
	v_readlane_b32 s1, v244, 21
	v_readlane_b32 vcc_lo, v244, 22
	v_readlane_b32 vcc_hi, v244, 23
	s_mov_b32 exec_lo, 0xffff0000
	s_mov_b32 exec_hi, 0x0
	v_mov_b32_e32 v170, s0
	v_mov_b32_e32 v176, s1
	v_mov_b32_e32 v177, vcc_lo
	v_mov_b32_e32 v191, vcc_hi
	s_mov_b64 exec, -1
	s_max_i32 s0, s0, 0
	s_max_i32 s1, s1, 0
	s_max_i32 vcc_lo, vcc_lo, 0
	s_max_i32 vcc_hi, vcc_hi, 0
	s_sub_i32 s1, s1, s0
	s_sub_i32 vcc_hi, vcc_hi, vcc_lo
	s_lshl_b32 s0, s0, 9
	s_lshl_b32 s1, s1, 9
	s_lshl_b32 vcc_lo, vcc_lo, 9
	s_lshl_b32 vcc_hi, vcc_hi, 9
	v_add_u32_e32 v136, s0, v246
	v_add_u32_e32 v140, vcc_lo, v246
	v_mad_i32_i24 v136, v115, s1, v136
	v_mad_i32_i24 v140, v115, vcc_hi, v140
	global_load_dwordx4 v[136:139], v136, s[2:3]
	global_load_dwordx4 v[140:143], v140, s[2:3]
	v_readlane_b32 s0, v244, 24
	v_readlane_b32 s1, v244, 25
	v_readlane_b32 vcc_lo, v244, 26
	v_readlane_b32 vcc_hi, v244, 27
	s_mov_b32 exec_lo, 0x0
	s_mov_b32 exec_hi, 0xffff
	v_mov_b32_e32 v170, s0
	v_mov_b32_e32 v176, s1
	v_mov_b32_e32 v177, vcc_lo
	v_mov_b32_e32 v191, vcc_hi
	s_mov_b64 exec, -1
	s_max_i32 s0, s0, 0
	s_max_i32 s1, s1, 0
	s_max_i32 vcc_lo, vcc_lo, 0
	s_max_i32 vcc_hi, vcc_hi, 0
	s_sub_i32 s1, s1, s0
	s_sub_i32 vcc_hi, vcc_hi, vcc_lo
	s_lshl_b32 s0, s0, 9
	s_lshl_b32 s1, s1, 9
	s_lshl_b32 vcc_lo, vcc_lo, 9
	s_lshl_b32 vcc_hi, vcc_hi, 9
	v_add_u32_e32 v228, s0, v246
	v_add_u32_e32 v232, vcc_lo, v246
	v_mad_i32_i24 v228, v115, s1, v228
	v_mad_i32_i24 v232, v115, vcc_hi, v232
	global_load_dwordx4 v[228:231], v228, s[2:3]
	global_load_dwordx4 v[232:235], v232, s[2:3]
	v_readlane_b32 s0, v244, 28
	v_readlane_b32 s1, v244, 29
	v_readlane_b32 vcc_lo, v244, 30
	v_readlane_b32 vcc_hi, v244, 31
	s_mov_b32 exec_lo, 0x0
	s_mov_b32 exec_hi, 0xffff0000
	v_mov_b32_e32 v170, s0
	v_mov_b32_e32 v176, s1
	v_mov_b32_e32 v177, vcc_lo
	v_mov_b32_e32 v191, vcc_hi
	s_mov_b64 exec, -1
	s_max_i32 s0, s0, 0
	s_max_i32 s1, s1, 0
	s_max_i32 vcc_lo, vcc_lo, 0
	s_max_i32 vcc_hi, vcc_hi, 0
	s_sub_i32 s1, s1, s0
	s_sub_i32 vcc_hi, vcc_hi, vcc_lo
	s_lshl_b32 s0, s0, 9
	s_lshl_b32 s1, s1, 9
	s_lshl_b32 vcc_lo, vcc_lo, 9
	s_lshl_b32 vcc_hi, vcc_hi, 9
	v_add_u32_e32 v236, s0, v246
	v_add_u32_e32 v240, vcc_lo, v246
	v_mad_i32_i24 v236, v115, s1, v236
	v_mad_i32_i24 v240, v115, vcc_hi, v240
	global_load_dwordx4 v[236:239], v236, s[2:3]
	global_load_dwordx4 v[240:243], v240, s[2:3]
	s_branch .Latt_nopf
